# P4 y_ret epilogue: loads of batches 1-3 requested a whole batch ahead into spare VGPRs, counted waits instead of vmcnt(0) (previous batch's stores stay in flight)
# speedup vs baseline: 1.0063x; 1.0027x over previous
.LBB0_696:
	v_lshlrev_b32_e32 v250, 1, v150
	v_lshl_add_u32 v250, v146, 12, v250
	s_lshl_b32 s98, s78, 3
	s_and_b32 s98, s98, -16
	s_lshl_b32 s98, s98, 2
	v_lshl_add_u32 v251, v148, 4, s98
	v_lshl_add_u32 v251, v146, 8, v251
	s_lshl_b32 s4, s78, 3
	s_and_b32 s4, s4, -16
	s_ashr_i32 s5, s4, 31
	s_lshl_b64 s[4:5], s[4:5], 2
	s_add_u32 s4, s60, s4
	s_addc_u32 s5, s61, s5
	v_ashrrev_i32_e32 v149, 31, v148
	v_lshl_add_u64 v[150:151], v[150:151], 1, s[0:1]
	v_lshlrev_b64 v[130:131], 12, v[146:147]
	v_lshl_add_u64 v[154:155], v[150:151], 0, v[130:131]
	v_lshl_add_u64 v[152:153], v[148:149], 4, s[4:5]
	v_lshlrev_b64 v[130:131], 8, v[146:147]
	v_lshl_add_u64 v[130:131], v[152:153], 0, v[130:131]
	global_load_dwordx4 v[164:167], v[154:155], off
	global_load_dwordx4 v[168:171], v[130:131], off
	v_add_u32_e32 v130, 16, v146
	v_ashrrev_i32_e32 v131, 31, v130
	v_lshlrev_b64 v[132:133], 8, v[130:131]
	v_lshl_add_u64 v[132:133], v[152:153], 0, v[132:133]
	global_load_dwordx4 v[172:175], v[132:133], off
	global_load_dwordx4 v[176:179], v[154:155], off offset:256
	v_mul_f32_e32 v132, 0xbfb8aa3b, v126
	v_mul_f32_e32 v135, 0xbfb8aa3b, v127
	v_mul_f32_e32 v133, 0xbfb8aa3b, v122
	v_mul_f32_e32 v156, 0xbfb8aa3b, v129
	v_mul_f32_e32 v157, 0xbfb8aa3b, v125
	v_exp_f32_e32 v163, v132
	v_exp_f32_e32 v135, v135
	v_lshlrev_b64 v[130:131], 12, v[130:131]
	v_exp_f32_e32 v184, v133
	v_exp_f32_e32 v185, v156
	v_exp_f32_e32 v186, v157
	v_lshl_add_u64 v[156:157], v[150:151], 0, v[130:131]
	global_load_dwordx4 v[180:183], v[156:157], off
	global_load_dwordx4 v[130:133], v[156:157], off offset:256
	v_add_u32_e32 v252, 0x20000, v250
	global_load_dwordx4 v[234:237], v252, s[0:1] offset:256
	global_load_dwordx4 v[238:241], v252, s[0:1]
	v_add_u32_e32 v253, 0x30000, v250
	global_load_dwordx4 v[242:245], v253, s[0:1] offset:256
	global_load_dwordx4 v[246:249], v253, s[0:1]
	v_add_u32_e32 v252, 0x3000, v251
	global_load_dwordx4 v[226:229], v252, s[60:61]
	v_add_u32_e32 v253, 0x2000, v251
	global_load_dwordx4 v[230:233], v253, s[60:61]
	v_add_f32_e32 v163, 1.0, v163
	v_add_f32_e32 v135, 1.0, v135
	v_add_f32_e32 v187, 1.0, v184
	v_add_f32_e32 v189, 1.0, v185
	v_rcp_f32_e32 v184, v163
	v_rcp_f32_e32 v185, v135
	v_mul_f32_e32 v137, 0xbfb8aa3b, v123
	v_mul_f32_e32 v147, 0xbfb8aa3b, v124
	v_exp_f32_e32 v137, v137
	v_pk_mul_f32 v[184:185], v[126:127], v[184:185]
	v_exp_f32_e32 v147, v147
	v_mov_b64_e32 v[148:149], s[38:39]
	v_mul_f32_e32 v139, 0xbfb8aa3b, v128
	v_exp_f32_e32 v139, v139
	v_add_f32_e32 v137, 1.0, v137
	v_add_f32_e32 v147, 1.0, v147
	v_add_f32_e32 v191, 1.0, v186
	v_rcp_f32_e32 v186, v187
	v_rcp_f32_e32 v187, v137
	v_rcp_f32_e32 v190, v147
	v_rcp_f32_e32 v191, v191
	v_add_f32_e32 v139, 1.0, v139
	v_rcp_f32_e32 v188, v139
	v_rcp_f32_e32 v189, v189
	v_pk_mul_f32 v[124:125], v[124:125], v[190:191]
	v_pk_mul_f32 v[122:123], v[122:123], v[186:187]
	v_pk_mul_f32 v[128:129], v[128:129], v[188:189]
	s_waitcnt vmcnt(6)
	v_lshlrev_b32_e32 v192, 16, v166
	v_mov_b32_e32 v126, v169
	v_mov_b32_e32 v127, v170
	v_mov_b32_e32 v169, v171
	v_pk_add_f32 v[126:127], v[126:127], v[168:169]
	v_and_b32_e32 v193, 0xffff0000, v166
	v_mov_b32_e32 v170, v173
	v_mov_b32_e32 v171, v174
	v_mov_b32_e32 v173, v175
	v_pk_add_f32 v[168:169], v[170:171], v[172:173]
	v_pk_add_f32 v[126:127], v[126:127], v[126:127] op_sel:[0,1] op_sel_hi:[1,0]
	v_pk_add_f32 v[168:169], v[168:169], v[168:169] op_sel:[0,1] op_sel_hi:[1,0]
	v_mov_b32_e32 v127, v126
	v_mov_b32_e32 v135, v168
	s_nop 0
	v_permlane16_swap_b32_e32 v126, v127
	v_permlane16_swap_b32_e32 v168, v135
	v_add_f32_e32 v127, v126, v127
	v_add_f32_e32 v126, v168, v135
	v_mov_b32_e32 v169, v127
	v_mov_b32_e32 v168, v126
	s_nop 0
	v_permlane32_swap_b32_e32 v127, v169
	v_permlane32_swap_b32_e32 v126, v168
	v_pk_add_f32 v[126:127], v[126:127], v[168:169]
	v_lshlrev_b32_e32 v166, 16, v167
	v_pk_fma_f32 v[126:127], v[126:127], s[36:37], v[148:149] op_sel_hi:[1,0,0]
	v_and_b32_e32 v167, 0xffff0000, v167
	v_mul_f32_e32 v135, 0x4b800000, v127
	v_cmp_gt_f32_e32 vcc, s76, v127
	v_pk_mul_f32 v[122:123], v[122:123], v[192:193]
	v_pk_mul_f32 v[124:125], v[124:125], v[166:167]
	v_cndmask_b32_e32 v127, v127, v135, vcc
	v_rsq_f32_e32 v127, v127
	v_lshlrev_b32_e32 v188, 16, v164
	v_and_b32_e32 v189, 0xffff0000, v164
	v_lshlrev_b32_e32 v164, 16, v165
	v_mul_f32_e32 v135, 0x45800000, v127
	v_cndmask_b32_e32 v168, v127, v135, vcc
	v_and_b32_e32 v165, 0xffff0000, v165
	v_pk_mul_f32 v[166:167], v[124:125], v[168:169] op_sel_hi:[1,0]
	v_pk_mul_f32 v[124:125], v[122:123], v[168:169] op_sel_hi:[1,0]
	v_pk_mul_f32 v[128:129], v[128:129], v[164:165]
	v_cvt_pk_bf16_f32 v124, v124, v125
	v_mul_f32_e32 v125, 0xbfb8aa3b, v118
	v_pk_mul_f32 v[128:129], v[128:129], v[168:169] op_sel_hi:[1,0]
	v_exp_f32_e32 v127, v125
	v_mul_f32_e32 v125, 0xbfb8aa3b, v114
	v_cvt_pk_bf16_f32 v123, v128, v129
	v_exp_f32_e32 v129, v125
	v_add_f32_e32 v127, 1.0, v127
	v_mul_f32_e32 v137, 0x4b800000, v126
	v_cmp_gt_f32_e64 s[4:5], s76, v126
	v_rcp_f32_e32 v128, v127
	v_add_f32_e32 v127, 1.0, v129
	v_mul_f32_e32 v129, 0xbfb8aa3b, v119
	v_cndmask_b32_e64 v126, v126, v137, s[4:5]
	v_exp_f32_e32 v129, v129
	v_mul_f32_e32 v135, 0xbfb8aa3b, v115
	v_rsq_f32_e32 v126, v126
	v_exp_f32_e32 v135, v135
	v_pk_mul_f32 v[170:171], v[184:185], v[188:189]
	v_cvt_pk_bf16_f32 v125, v166, v167
	v_pk_mul_f32 v[164:165], v[170:171], v[168:169] op_sel_hi:[1,0]
	v_mul_f32_e32 v137, 0x45800000, v126
	v_cvt_pk_bf16_f32 v122, v164, v165
	v_rcp_f32_e32 v164, v127
	v_add_f32_e32 v127, 1.0, v129
	v_rcp_f32_e32 v129, v127
	v_add_f32_e32 v127, 1.0, v135
	v_mul_f32_e32 v135, 0xbfb8aa3b, v120
	v_cndmask_b32_e64 v126, v126, v137, s[4:5]
	v_exp_f32_e32 v135, v135
	v_mul_f32_e32 v137, 0xbfb8aa3b, v116
	v_exp_f32_e32 v137, v137
	v_rcp_f32_e32 v165, v127
	v_add_f32_e32 v127, 1.0, v135
	v_mul_f32_e32 v135, 0xbfb8aa3b, v121
	v_rcp_f32_e32 v166, v127
	v_add_f32_e32 v127, 1.0, v137
	v_exp_f32_e32 v135, v135
	v_mul_f32_e32 v137, 0xbfb8aa3b, v117
	v_exp_f32_e32 v137, v137
	v_rcp_f32_e32 v170, v127
	v_add_f32_e32 v127, 1.0, v135
	v_rcp_f32_e32 v167, v127
	v_add_f32_e32 v127, 1.0, v137
	v_rcp_f32_e32 v171, v127
	v_lshlrev_b32_e32 v172, 16, v176
	v_and_b32_e32 v173, 0xffff0000, v176
	v_lshlrev_b32_e32 v174, 16, v177
	v_and_b32_e32 v175, 0xffff0000, v177
	v_lshlrev_b32_e32 v176, 16, v178
	v_and_b32_e32 v177, 0xffff0000, v178
	v_lshlrev_b32_e32 v178, 16, v179
	v_and_b32_e32 v179, 0xffff0000, v179
	v_pk_mul_f32 v[116:117], v[116:117], v[170:171]
	v_pk_mul_f32 v[114:115], v[114:115], v[164:165]
	v_pk_mul_f32 v[118:119], v[118:119], v[128:129]
	v_pk_mul_f32 v[114:115], v[114:115], v[176:177]
	v_pk_mul_f32 v[116:117], v[116:117], v[178:179]
	v_pk_mul_f32 v[120:121], v[120:121], v[166:167]
	v_pk_mul_f32 v[118:119], v[118:119], v[172:173]
	v_pk_mul_f32 v[128:129], v[116:117], v[168:169] op_sel_hi:[1,0]
	v_pk_mul_f32 v[116:117], v[114:115], v[168:169] op_sel_hi:[1,0]
	v_pk_mul_f32 v[120:121], v[120:121], v[174:175]
	v_pk_mul_f32 v[118:119], v[118:119], v[168:169] op_sel_hi:[1,0]
	v_cvt_pk_bf16_f32 v116, v116, v117
	v_mul_f32_e32 v117, 0xbfb8aa3b, v110
	v_pk_mul_f32 v[120:121], v[120:121], v[168:169] op_sel_hi:[1,0]
	v_cvt_pk_bf16_f32 v114, v118, v119
	v_exp_f32_e32 v118, v117
	v_mul_f32_e32 v117, 0xbfb8aa3b, v106
	v_cvt_pk_bf16_f32 v115, v120, v121
	v_exp_f32_e32 v119, v117
	v_mul_f32_e32 v120, 0xbfb8aa3b, v111
	v_mul_f32_e32 v121, 0xbfb8aa3b, v107
	v_exp_f32_e32 v120, v120
	v_exp_f32_e32 v121, v121
	v_add_f32_e32 v119, 1.0, v119
	v_cvt_pk_bf16_f32 v117, v128, v129
	v_rcp_f32_e32 v128, v119
	v_add_f32_e32 v119, 1.0, v120
	v_add_f32_e32 v120, 1.0, v121
	v_mul_f32_e32 v121, 0xbfb8aa3b, v112
	v_mul_f32_e32 v127, 0xbfb8aa3b, v108
	v_exp_f32_e32 v121, v121
	v_exp_f32_e32 v127, v127
	v_rcp_f32_e32 v129, v120
	v_add_f32_e32 v118, 1.0, v118
	v_add_f32_e32 v120, 1.0, v121
	v_add_f32_e32 v121, 1.0, v127
	v_mul_f32_e32 v127, 0xbfb8aa3b, v113
	v_exp_f32_e32 v127, v127
	v_rcp_f32_e32 v164, v121
	v_rcp_f32_e32 v118, v118
	v_rcp_f32_e32 v119, v119
	v_add_f32_e32 v121, 1.0, v127
	v_rcp_f32_e32 v120, v120
	v_rcp_f32_e32 v121, v121
	v_add_u32_e32 v174, 48, v146
	v_add_u32_e32 v176, 32, v146
	v_lshlrev_b32_e32 v166, 16, v180
	v_and_b32_e32 v167, 0xffff0000, v180
	v_lshlrev_b32_e32 v168, 16, v181
	v_and_b32_e32 v169, 0xffff0000, v181
	v_pk_mul_f32 v[112:113], v[112:113], v[120:121]
	v_pk_mul_f32 v[110:111], v[110:111], v[118:119]
	v_ashrrev_i32_e32 v175, 31, v174
	v_ashrrev_i32_e32 v177, 31, v176
	v_pk_mul_f32 v[166:167], v[110:111], v[166:167]
	v_pk_mul_f32 v[168:169], v[112:113], v[168:169]
	v_lshlrev_b64 v[110:111], 8, v[174:175]
	v_lshlrev_b64 v[112:113], 8, v[176:177]
	v_lshl_add_u64 v[110:111], v[152:153], 0, v[110:111]
	v_lshl_add_u64 v[118:119], v[152:153], 0, v[112:113]
	s_nop 0
	v_mul_f32_e32 v135, 0xbfb8aa3b, v109
	v_exp_f32_e32 v135, v135
	v_lshlrev_b32_e32 v170, 16, v182
	v_and_b32_e32 v171, 0xffff0000, v182
	v_lshlrev_b32_e32 v172, 16, v183
	v_add_f32_e32 v127, 1.0, v135
	v_rcp_f32_e32 v165, v127
	v_and_b32_e32 v173, 0xffff0000, v183
	v_pk_mul_f32 v[106:107], v[106:107], v[128:129]
	v_pk_mul_f32 v[166:167], v[166:167], v[126:127] op_sel_hi:[1,0]
	v_pk_mul_f32 v[108:109], v[108:109], v[164:165]
	v_pk_mul_f32 v[106:107], v[106:107], v[170:171]
	v_pk_mul_f32 v[108:109], v[108:109], v[172:173]
	v_pk_mul_f32 v[106:107], v[106:107], v[126:127] op_sel_hi:[1,0]
	v_pk_mul_f32 v[108:109], v[108:109], v[126:127] op_sel_hi:[1,0]
	v_cvt_pk_bf16_f32 v164, v166, v167
	v_cvt_pk_bf16_f32 v166, v106, v107
	v_mul_f32_e32 v107, 0xbfb8aa3b, v98
	v_cvt_pk_bf16_f32 v167, v108, v109
	v_mul_f32_e32 v108, 0xbfb8aa3b, v103
	v_exp_f32_e32 v107, v107
	v_exp_f32_e32 v109, v108
	v_mul_f32_e32 v108, 0xbfb8aa3b, v99
	v_pk_mul_f32 v[168:169], v[168:169], v[126:127] op_sel_hi:[1,0]
	v_exp_f32_e32 v127, v108
	v_add_f32_e32 v107, 1.0, v107
	v_rcp_f32_e32 v108, v107
	v_add_f32_e32 v107, 1.0, v109
	v_add_f32_e32 v109, 1.0, v127
	v_mul_f32_e32 v127, 0xbfb8aa3b, v104
	v_exp_f32_e32 v127, v127
	v_mul_f32_e32 v128, 0xbfb8aa3b, v100
	v_exp_f32_e32 v129, v128
	v_mul_f32_e32 v106, 0xbfb8aa3b, v102
	v_add_f32_e32 v127, 1.0, v127
	v_rcp_f32_e32 v128, v127
	v_add_f32_e32 v127, 1.0, v129
	v_mul_f32_e32 v129, 0xbfb8aa3b, v105
	v_exp_f32_e32 v129, v129
	v_mul_f32_e32 v135, 0xbfb8aa3b, v101
	v_exp_f32_e32 v106, v106
	v_exp_f32_e32 v135, v135
	v_rcp_f32_e32 v109, v109
	v_cvt_pk_bf16_f32 v165, v168, v169
	v_rcp_f32_e32 v168, v127
	v_add_f32_e32 v127, 1.0, v129
	v_add_f32_e32 v106, 1.0, v106
	v_rcp_f32_e32 v129, v127
	v_add_f32_e32 v127, 1.0, v135
	v_rcp_f32_e32 v106, v106
	v_rcp_f32_e32 v107, v107
	v_rcp_f32_e32 v169, v127
	v_lshlrev_b32_e32 v172, 16, v132
	v_and_b32_e32 v173, 0xffff0000, v132
	v_pk_mul_f32 v[98:99], v[98:99], v[108:109]
	v_pk_mul_f32 v[104:105], v[104:105], v[128:129]
	v_pk_mul_f32 v[98:99], v[98:99], v[172:173]
	v_lshlrev_b32_e32 v170, 16, v130
	v_pk_mul_f32 v[98:99], v[98:99], v[126:127] op_sel_hi:[1,0]
	v_and_b32_e32 v171, 0xffff0000, v130
	v_cvt_pk_bf16_f32 v128, v98, v99
	v_lshlrev_b64 v[98:99], 12, v[176:177]
	v_lshlrev_b32_e32 v130, 16, v131
	v_and_b32_e32 v131, 0xffff0000, v131
	v_lshlrev_b32_e32 v132, 16, v133
	v_and_b32_e32 v133, 0xffff0000, v133
	v_pk_mul_f32 v[102:103], v[102:103], v[106:107]
	v_pk_mul_f32 v[100:101], v[100:101], v[168:169]
	v_lshl_add_u64 v[108:109], v[150:151], 0, v[98:99]
	v_pk_mul_f32 v[102:103], v[102:103], v[170:171]
	v_pk_mul_f32 v[104:105], v[104:105], v[130:131]
	v_pk_mul_f32 v[100:101], v[100:101], v[132:133]
	v_lshlrev_b64 v[98:99], 12, v[174:175]
	v_pk_mul_f32 v[104:105], v[104:105], v[126:127] op_sel_hi:[1,0]
	v_pk_mul_f32 v[102:103], v[102:103], v[126:127] op_sel_hi:[1,0]
	v_pk_mul_f32 v[100:101], v[100:101], v[126:127] op_sel_hi:[1,0]
	v_lshl_add_u64 v[106:107], v[150:151], 0, v[98:99]
	v_cvt_pk_bf16_f32 v126, v102, v103
	v_cvt_pk_bf16_f32 v127, v104, v105
	v_cvt_pk_bf16_f32 v129, v100, v101
	s_waitcnt vmcnt(0)
	v_mov_b32_e32 v110, v226
	v_mov_b32_e32 v111, v227
	v_mov_b32_e32 v112, v228
	v_mov_b32_e32 v113, v229
	v_mov_b32_e32 v118, v230
	v_mov_b32_e32 v119, v231
	v_mov_b32_e32 v120, v232
	v_mov_b32_e32 v121, v233
	v_mov_b32_e32 v130, v234
	v_mov_b32_e32 v131, v235
	v_mov_b32_e32 v132, v236
	v_mov_b32_e32 v133, v237
	v_mov_b32_e32 v168, v238
	v_mov_b32_e32 v169, v239
	v_mov_b32_e32 v170, v240
	v_mov_b32_e32 v171, v241
	v_mov_b32_e32 v98, v242
	v_mov_b32_e32 v99, v243
	v_mov_b32_e32 v100, v244
	v_mov_b32_e32 v101, v245
	v_mov_b32_e32 v102, v246
	v_mov_b32_e32 v103, v247
	v_mov_b32_e32 v104, v248
	v_mov_b32_e32 v105, v249
	v_add_u32_e32 v252, 0x80000, v250
	global_load_dwordx4 v[234:237], v252, s[0:1] offset:256
	global_load_dwordx4 v[238:241], v252, s[0:1]
	v_add_u32_e32 v253, 0x90000, v250
	global_load_dwordx4 v[242:245], v253, s[0:1] offset:256
	global_load_dwordx4 v[246:249], v253, s[0:1]
	v_add_u32_e32 v252, 0x9000, v251
	global_load_dwordx4 v[226:229], v252, s[60:61]
	v_add_u32_e32 v253, 0x8000, v251
	global_load_dwordx4 v[230:233], v253, s[60:61]
	s_nop 0
	global_store_dwordx4 v[154:155], v[122:125], off
	global_store_dwordx4 v[154:155], v[114:117], off offset:256
	global_store_dwordx4 v[156:157], v[164:167], off
	global_store_dwordx4 v[156:157], v[126:129], off offset:256
	s_waitcnt vmcnt(10)
	v_mov_b32_e32 v114, v119
	v_mov_b32_e32 v115, v120
	v_mov_b32_e32 v119, v121
	v_pk_add_f32 v[114:115], v[114:115], v[118:119]
	v_mov_b32_e32 v118, v111
	v_mov_b32_e32 v119, v112
	v_mov_b32_e32 v111, v113
	v_pk_add_f32 v[110:111], v[118:119], v[110:111]
	v_pk_add_f32 v[114:115], v[114:115], v[114:115] op_sel:[0,1] op_sel_hi:[1,0]
	v_pk_add_f32 v[110:111], v[110:111], v[110:111] op_sel:[0,1] op_sel_hi:[1,0]
	v_mov_b32_e32 v115, v114
	v_mov_b32_e32 v111, v110
	s_nop 0
	v_permlane16_swap_b32_e32 v114, v115
	v_permlane16_swap_b32_e32 v110, v111
	v_add_f32_e32 v115, v114, v115
	v_add_f32_e32 v114, v110, v111
	v_mov_b32_e32 v117, v115
	v_mov_b32_e32 v116, v114
	s_nop 0
	v_permlane32_swap_b32_e32 v115, v117
	v_permlane32_swap_b32_e32 v114, v116
	v_pk_add_f32 v[110:111], v[114:115], v[116:117]
	v_mul_f32_e32 v113, 0xbfb8aa3b, v94
	v_pk_fma_f32 v[110:111], v[110:111], s[36:37], v[148:149] op_sel_hi:[1,0,0]
	v_exp_f32_e32 v113, v113
	v_mul_f32_e32 v112, 0x4b800000, v111
	v_cmp_gt_f32_e32 vcc, s76, v111
	v_cmp_gt_f32_e64 s[4:5], s76, v110
	v_mul_f32_e32 v114, 0xbfb8aa3b, v90
	v_cndmask_b32_e32 v111, v111, v112, vcc
	v_mul_f32_e32 v112, 0x4b800000, v110
	v_rsq_f32_e32 v111, v111
	v_cndmask_b32_e64 v110, v110, v112, s[4:5]
	v_rsq_f32_e32 v110, v110
	v_exp_f32_e32 v115, v114
	v_mul_f32_e32 v112, 0x45800000, v111
	v_cndmask_b32_e32 v112, v111, v112, vcc
	v_mul_f32_e32 v111, 0x45800000, v110
	v_cndmask_b32_e64 v110, v110, v111, s[4:5]
	v_add_f32_e32 v111, 1.0, v113
	v_mul_f32_e32 v113, 0xbfb8aa3b, v95
	v_rcp_f32_e32 v114, v111
	v_add_f32_e32 v111, 1.0, v115
	v_exp_f32_e32 v113, v113
	v_mul_f32_e32 v115, 0xbfb8aa3b, v91
	v_exp_f32_e32 v117, v115
	v_rcp_f32_e32 v116, v111
	v_add_f32_e32 v111, 1.0, v113
	v_mul_f32_e32 v113, 0xbfb8aa3b, v96
	v_rcp_f32_e32 v115, v111
	v_add_f32_e32 v111, 1.0, v117
	v_exp_f32_e32 v113, v113
	v_mul_f32_e32 v117, 0xbfb8aa3b, v92
	v_exp_f32_e32 v119, v117
	v_rcp_f32_e32 v117, v111
	v_add_f32_e32 v111, 1.0, v113
	v_mul_f32_e32 v113, 0xbfb8aa3b, v97
	v_rcp_f32_e32 v118, v111
	v_add_f32_e32 v111, 1.0, v119
	v_exp_f32_e32 v113, v113
	v_mul_f32_e32 v119, 0xbfb8aa3b, v93
	v_exp_f32_e32 v121, v119
	v_rcp_f32_e32 v120, v111
	v_add_f32_e32 v111, 1.0, v113
	v_rcp_f32_e32 v119, v111
	v_add_f32_e32 v111, 1.0, v121
	v_rcp_f32_e32 v121, v111
	v_lshlrev_b32_e32 v126, 16, v170
	v_and_b32_e32 v127, 0xffff0000, v170
	v_lshlrev_b32_e32 v128, 16, v171
	v_and_b32_e32 v129, 0xffff0000, v171
	v_pk_mul_f32 v[92:93], v[92:93], v[120:121]
	v_pk_mul_f32 v[90:91], v[90:91], v[116:117]
	v_lshlrev_b32_e32 v122, 16, v168
	v_and_b32_e32 v123, 0xffff0000, v168
	v_lshlrev_b32_e32 v124, 16, v169
	v_and_b32_e32 v125, 0xffff0000, v169
	v_pk_mul_f32 v[96:97], v[96:97], v[118:119]
	v_pk_mul_f32 v[94:95], v[94:95], v[114:115]
	v_pk_mul_f32 v[90:91], v[90:91], v[126:127]
	v_pk_mul_f32 v[92:93], v[92:93], v[128:129]
	v_pk_mul_f32 v[94:95], v[94:95], v[122:123]
	v_pk_mul_f32 v[96:97], v[96:97], v[124:125]
	v_pk_mul_f32 v[114:115], v[92:93], v[112:113] op_sel_hi:[1,0]
	v_pk_mul_f32 v[92:93], v[90:91], v[112:113] op_sel_hi:[1,0]
	v_pk_mul_f32 v[96:97], v[96:97], v[112:113] op_sel_hi:[1,0]
	v_pk_mul_f32 v[94:95], v[94:95], v[112:113] op_sel_hi:[1,0]
	v_cvt_pk_bf16_f32 v92, v92, v93
	v_mul_f32_e32 v93, 0xbfb8aa3b, v86
	v_cvt_pk_bf16_f32 v90, v94, v95
	v_cvt_pk_bf16_f32 v91, v96, v97
	v_exp_f32_e32 v94, v93
	v_mul_f32_e32 v93, 0xbfb8aa3b, v82
	v_mul_f32_e32 v96, 0xbfb8aa3b, v87
	v_exp_f32_e32 v95, v93
	v_exp_f32_e32 v97, v96
	v_mul_f32_e32 v96, 0xbfb8aa3b, v83
	v_exp_f32_e32 v111, v96
	v_add_f32_e32 v95, 1.0, v95
	v_rcp_f32_e32 v96, v95
	v_add_f32_e32 v95, 1.0, v97
	v_add_f32_e32 v97, 1.0, v111
	v_mul_f32_e32 v111, 0xbfb8aa3b, v88
	v_exp_f32_e32 v111, v111
	v_mul_f32_e32 v113, 0xbfb8aa3b, v84
	v_exp_f32_e32 v113, v113
	v_cvt_pk_bf16_f32 v93, v114, v115
	v_add_f32_e32 v111, 1.0, v111
	v_rcp_f32_e32 v114, v111
	v_add_f32_e32 v111, 1.0, v113
	v_mul_f32_e32 v113, 0xbfb8aa3b, v89
	v_exp_f32_e32 v113, v113
	v_mul_f32_e32 v115, 0xbfb8aa3b, v85
	v_exp_f32_e32 v117, v115
	v_rcp_f32_e32 v116, v111
	v_add_f32_e32 v111, 1.0, v113
	v_rcp_f32_e32 v115, v111
	v_add_f32_e32 v111, 1.0, v117
	v_add_f32_e32 v94, 1.0, v94
	v_rcp_f32_e32 v97, v97
	v_rcp_f32_e32 v117, v111
	v_rcp_f32_e32 v94, v94
	v_rcp_f32_e32 v95, v95
	v_lshlrev_b32_e32 v122, 16, v132
	v_and_b32_e32 v123, 0xffff0000, v132
	v_lshlrev_b32_e32 v124, 16, v133
	v_and_b32_e32 v125, 0xffff0000, v133
	v_pk_mul_f32 v[84:85], v[84:85], v[116:117]
	v_pk_mul_f32 v[82:83], v[82:83], v[96:97]
	v_lshlrev_b32_e32 v118, 16, v130
	v_and_b32_e32 v119, 0xffff0000, v130
	v_pk_mul_f32 v[86:87], v[86:87], v[94:95]
	v_pk_mul_f32 v[82:83], v[82:83], v[122:123]
	v_pk_mul_f32 v[84:85], v[84:85], v[124:125]
	v_lshlrev_b32_e32 v120, 16, v131
	v_and_b32_e32 v121, 0xffff0000, v131
	v_pk_mul_f32 v[88:89], v[88:89], v[114:115]
	v_pk_mul_f32 v[86:87], v[86:87], v[118:119]
	v_pk_mul_f32 v[94:95], v[84:85], v[112:113] op_sel_hi:[1,0]
	v_pk_mul_f32 v[84:85], v[82:83], v[112:113] op_sel_hi:[1,0]
	v_pk_mul_f32 v[88:89], v[88:89], v[120:121]
	v_pk_mul_f32 v[86:87], v[86:87], v[112:113] op_sel_hi:[1,0]
	v_cvt_pk_bf16_f32 v84, v84, v85
	v_mul_f32_e32 v85, 0xbfb8aa3b, v78
	v_pk_mul_f32 v[88:89], v[88:89], v[112:113] op_sel_hi:[1,0]
	v_cvt_pk_bf16_f32 v82, v86, v87
	v_exp_f32_e32 v86, v85
	v_mul_f32_e32 v85, 0xbfb8aa3b, v74
	v_cvt_pk_bf16_f32 v83, v88, v89
	v_exp_f32_e32 v87, v85
	v_mul_f32_e32 v88, 0xbfb8aa3b, v79
	v_mul_f32_e32 v89, 0xbfb8aa3b, v75
	v_exp_f32_e32 v88, v88
	v_exp_f32_e32 v89, v89
	v_add_f32_e32 v87, 1.0, v87
	v_cvt_pk_bf16_f32 v85, v94, v95
	v_rcp_f32_e32 v94, v87
	v_add_f32_e32 v87, 1.0, v88
	v_add_f32_e32 v88, 1.0, v89
	v_mul_f32_e32 v89, 0xbfb8aa3b, v80
	v_mul_f32_e32 v95, 0xbfb8aa3b, v76
	v_exp_f32_e32 v89, v89
	v_exp_f32_e32 v96, v95
	v_rcp_f32_e32 v95, v88
	v_add_f32_e32 v86, 1.0, v86
	v_add_f32_e32 v88, 1.0, v89
	v_add_f32_e32 v89, 1.0, v96
	v_mul_f32_e32 v96, 0xbfb8aa3b, v81
	v_exp_f32_e32 v97, v96
	v_mul_f32_e32 v96, 0xbfb8aa3b, v77
	v_exp_f32_e32 v111, v96
	v_rcp_f32_e32 v96, v89
	v_add_f32_e32 v89, 1.0, v97
	v_rcp_f32_e32 v86, v86
	v_rcp_f32_e32 v87, v87
	v_rcp_f32_e32 v88, v88
	v_rcp_f32_e32 v89, v89
	v_add_u32_e32 v116, 0x90, v146
	v_add_u32_e32 v118, 0x80, v146
	v_lshlrev_b32_e32 v112, 16, v102
	v_and_b32_e32 v113, 0xffff0000, v102
	v_lshlrev_b32_e32 v102, 16, v103
	v_and_b32_e32 v103, 0xffff0000, v103
	v_pk_mul_f32 v[80:81], v[80:81], v[88:89]
	v_pk_mul_f32 v[78:79], v[78:79], v[86:87]
	v_ashrrev_i32_e32 v117, 31, v116
	v_ashrrev_i32_e32 v119, 31, v118
	v_pk_mul_f32 v[112:113], v[78:79], v[112:113]
	v_pk_mul_f32 v[102:103], v[80:81], v[102:103]
	v_lshlrev_b64 v[78:79], 8, v[116:117]
	v_lshlrev_b64 v[80:81], 8, v[118:119]
	v_lshl_add_u64 v[78:79], v[152:153], 0, v[78:79]
	v_lshl_add_u64 v[86:87], v[152:153], 0, v[80:81]
	s_nop 0
	v_add_f32_e32 v97, 1.0, v111
	v_rcp_f32_e32 v97, v97
	v_lshlrev_b32_e32 v114, 16, v104
	v_and_b32_e32 v115, 0xffff0000, v104
	v_lshlrev_b32_e32 v104, 16, v105
	v_and_b32_e32 v105, 0xffff0000, v105
	v_pk_mul_f32 v[76:77], v[76:77], v[96:97]
	v_pk_mul_f32 v[74:75], v[74:75], v[94:95]
	v_pk_mul_f32 v[76:77], v[76:77], v[104:105]
	v_pk_mul_f32 v[74:75], v[74:75], v[114:115]
	v_pk_mul_f32 v[76:77], v[76:77], v[110:111] op_sel_hi:[1,0]
	v_pk_mul_f32 v[74:75], v[74:75], v[110:111] op_sel_hi:[1,0]
	v_cvt_pk_bf16_f32 v97, v76, v77
	v_cvt_pk_bf16_f32 v96, v74, v75
	v_mul_f32_e32 v75, 0xbfb8aa3b, v66
	v_mul_f32_e32 v76, 0xbfb8aa3b, v71
	v_pk_mul_f32 v[102:103], v[102:103], v[110:111] op_sel_hi:[1,0]
	v_exp_f32_e32 v75, v75
	v_exp_f32_e32 v77, v76
	v_mul_f32_e32 v76, 0xbfb8aa3b, v67
	v_cvt_pk_bf16_f32 v95, v102, v103
	v_exp_f32_e32 v102, v76
	v_mul_f32_e32 v103, 0xbfb8aa3b, v68
	v_mul_f32_e32 v104, 0xbfb8aa3b, v73
	v_add_f32_e32 v75, 1.0, v75
	v_exp_f32_e32 v103, v103
	v_exp_f32_e32 v105, v104
	v_mul_f32_e32 v104, 0xbfb8aa3b, v69
	v_pk_mul_f32 v[112:113], v[112:113], v[110:111] op_sel_hi:[1,0]
	v_mul_f32_e32 v74, 0xbfb8aa3b, v70
	v_rcp_f32_e32 v76, v75
	v_add_f32_e32 v75, 1.0, v77
	v_add_f32_e32 v77, 1.0, v102
	v_mul_f32_e32 v102, 0xbfb8aa3b, v72
	v_exp_f32_e32 v111, v104
	v_exp_f32_e32 v74, v74
	v_exp_f32_e32 v102, v102
	v_rcp_f32_e32 v77, v77
	v_add_f32_e32 v103, 1.0, v103
	v_rcp_f32_e32 v104, v103
	v_add_f32_e32 v103, 1.0, v105
	v_add_f32_e32 v105, 1.0, v111
	v_add_f32_e32 v74, 1.0, v74
	v_add_f32_e32 v102, 1.0, v102
	v_rcp_f32_e32 v105, v105
	v_rcp_f32_e32 v74, v74
	v_rcp_f32_e32 v75, v75
	v_rcp_f32_e32 v102, v102
	v_rcp_f32_e32 v103, v103
	v_lshlrev_b32_e32 v114, 16, v100
	v_and_b32_e32 v115, 0xffff0000, v100
	v_pk_mul_f32 v[66:67], v[66:67], v[76:77]
	v_lshlrev_b32_e32 v100, 16, v101
	v_pk_mul_f32 v[66:67], v[66:67], v[114:115]
	v_and_b32_e32 v101, 0xffff0000, v101
	v_pk_mul_f32 v[68:69], v[68:69], v[104:105]
	v_pk_mul_f32 v[66:67], v[66:67], v[110:111] op_sel_hi:[1,0]
	v_cvt_pk_bf16_f32 v94, v112, v113
	v_lshlrev_b32_e32 v112, 16, v98
	v_and_b32_e32 v113, 0xffff0000, v98
	v_lshlrev_b32_e32 v98, 16, v99
	v_and_b32_e32 v99, 0xffff0000, v99
	v_pk_mul_f32 v[72:73], v[72:73], v[102:103]
	v_pk_mul_f32 v[70:71], v[70:71], v[74:75]
	v_pk_mul_f32 v[68:69], v[68:69], v[100:101]
	v_cvt_pk_bf16_f32 v100, v66, v67
	v_lshlrev_b64 v[66:67], 12, v[118:119]
	v_pk_mul_f32 v[70:71], v[70:71], v[112:113]
	v_pk_mul_f32 v[72:73], v[72:73], v[98:99]
	v_lshl_add_u64 v[74:75], v[150:151], 0, v[66:67]
	v_pk_mul_f32 v[72:73], v[72:73], v[110:111] op_sel_hi:[1,0]
	v_pk_mul_f32 v[70:71], v[70:71], v[110:111] op_sel_hi:[1,0]
	v_pk_mul_f32 v[68:69], v[68:69], v[110:111] op_sel_hi:[1,0]
	v_lshlrev_b64 v[66:67], 12, v[116:117]
	v_lshl_add_u64 v[76:77], v[150:151], 0, v[66:67]
	v_cvt_pk_bf16_f32 v98, v70, v71
	v_cvt_pk_bf16_f32 v99, v72, v73
	v_cvt_pk_bf16_f32 v101, v68, v69
	s_waitcnt vmcnt(4)
	v_mov_b32_e32 v78, v226
	v_mov_b32_e32 v79, v227
	v_mov_b32_e32 v80, v228
	v_mov_b32_e32 v81, v229
	v_mov_b32_e32 v86, v230
	v_mov_b32_e32 v87, v231
	v_mov_b32_e32 v88, v232
	v_mov_b32_e32 v89, v233
	v_mov_b32_e32 v102, v234
	v_mov_b32_e32 v103, v235
	v_mov_b32_e32 v104, v236
	v_mov_b32_e32 v105, v237
	v_mov_b32_e32 v110, v238
	v_mov_b32_e32 v111, v239
	v_mov_b32_e32 v112, v240
	v_mov_b32_e32 v113, v241
	v_mov_b32_e32 v66, v242
	v_mov_b32_e32 v67, v243
	v_mov_b32_e32 v68, v244
	v_mov_b32_e32 v69, v245
	v_mov_b32_e32 v70, v246
	v_mov_b32_e32 v71, v247
	v_mov_b32_e32 v72, v248
	v_mov_b32_e32 v73, v249
	v_add_u32_e32 v252, 0xa0000, v250
	global_load_dwordx4 v[234:237], v252, s[0:1] offset:256
	global_load_dwordx4 v[238:241], v252, s[0:1]
	v_add_u32_e32 v253, 0xb0000, v250
	global_load_dwordx4 v[242:245], v253, s[0:1] offset:256
	global_load_dwordx4 v[246:249], v253, s[0:1]
	v_add_u32_e32 v252, 0xb000, v251
	global_load_dwordx4 v[226:229], v252, s[60:61]
	v_add_u32_e32 v253, 0xa000, v251
	global_load_dwordx4 v[230:233], v253, s[60:61]
	s_nop 0
	global_store_dwordx4 v[108:109], v[90:93], off
	global_store_dwordx4 v[108:109], v[82:85], off offset:256
	global_store_dwordx4 v[106:107], v[94:97], off
	global_store_dwordx4 v[106:107], v[98:101], off offset:256
	s_waitcnt vmcnt(10)
	v_mov_b32_e32 v82, v87
	v_mov_b32_e32 v83, v88
	v_mov_b32_e32 v87, v89
	v_pk_add_f32 v[82:83], v[82:83], v[86:87]
	v_mov_b32_e32 v86, v79
	v_mov_b32_e32 v87, v80
	v_mov_b32_e32 v79, v81
	v_pk_add_f32 v[78:79], v[86:87], v[78:79]
	v_pk_add_f32 v[82:83], v[82:83], v[82:83] op_sel:[0,1] op_sel_hi:[1,0]
	v_pk_add_f32 v[78:79], v[78:79], v[78:79] op_sel:[0,1] op_sel_hi:[1,0]
	v_mov_b32_e32 v83, v82
	v_mov_b32_e32 v79, v78
	s_nop 0
	v_permlane16_swap_b32_e32 v82, v83
	v_permlane16_swap_b32_e32 v78, v79
	v_add_f32_e32 v83, v82, v83
	v_add_f32_e32 v82, v78, v79
	v_mov_b32_e32 v85, v83
	v_mov_b32_e32 v84, v82
	s_nop 0
	v_permlane32_swap_b32_e32 v83, v85
	v_permlane32_swap_b32_e32 v82, v84
	v_pk_add_f32 v[78:79], v[82:83], v[84:85]
	v_mul_f32_e32 v81, 0xbfb8aa3b, v62
	v_pk_fma_f32 v[78:79], v[78:79], s[36:37], v[148:149] op_sel_hi:[1,0,0]
	v_exp_f32_e32 v81, v81
	v_mul_f32_e32 v80, 0x4b800000, v79
	v_cmp_gt_f32_e32 vcc, s76, v79
	v_cmp_gt_f32_e64 s[4:5], s76, v78
	v_mul_f32_e32 v82, 0xbfb8aa3b, v58
	v_cndmask_b32_e32 v79, v79, v80, vcc
	v_mul_f32_e32 v80, 0x4b800000, v78
	v_rsq_f32_e32 v79, v79
	v_cndmask_b32_e64 v78, v78, v80, s[4:5]
	v_rsq_f32_e32 v78, v78
	v_exp_f32_e32 v83, v82
	v_mul_f32_e32 v80, 0x45800000, v79
	v_cndmask_b32_e32 v80, v79, v80, vcc
	v_mul_f32_e32 v79, 0x45800000, v78
	v_cndmask_b32_e64 v78, v78, v79, s[4:5]
	v_add_f32_e32 v79, 1.0, v81
	v_mul_f32_e32 v81, 0xbfb8aa3b, v63
	v_rcp_f32_e32 v82, v79
	v_add_f32_e32 v79, 1.0, v83
	v_exp_f32_e32 v81, v81
	v_mul_f32_e32 v83, 0xbfb8aa3b, v59
	v_exp_f32_e32 v85, v83
	v_rcp_f32_e32 v84, v79
	v_add_f32_e32 v79, 1.0, v81
	v_mul_f32_e32 v81, 0xbfb8aa3b, v64
	v_rcp_f32_e32 v83, v79
	v_add_f32_e32 v79, 1.0, v85
	v_exp_f32_e32 v81, v81
	v_mul_f32_e32 v85, 0xbfb8aa3b, v60
	v_exp_f32_e32 v87, v85
	v_rcp_f32_e32 v85, v79
	v_add_f32_e32 v79, 1.0, v81
	v_mul_f32_e32 v81, 0xbfb8aa3b, v65
	v_rcp_f32_e32 v86, v79
	v_add_f32_e32 v79, 1.0, v87
	v_exp_f32_e32 v81, v81
	v_mul_f32_e32 v87, 0xbfb8aa3b, v61
	v_exp_f32_e32 v89, v87
	v_rcp_f32_e32 v88, v79
	v_add_f32_e32 v79, 1.0, v81
	v_rcp_f32_e32 v87, v79
	v_add_f32_e32 v79, 1.0, v89
	v_rcp_f32_e32 v89, v79
	v_pk_mul_f32 v[58:59], v[58:59], v[84:85]
	v_lshlrev_b32_e32 v94, 16, v112
	v_and_b32_e32 v95, 0xffff0000, v112
	v_lshlrev_b32_e32 v96, 16, v113
	v_and_b32_e32 v97, 0xffff0000, v113
	v_pk_mul_f32 v[60:61], v[60:61], v[88:89]
	v_lshlrev_b32_e32 v90, 16, v110
	v_and_b32_e32 v91, 0xffff0000, v110
	v_lshlrev_b32_e32 v92, 16, v111
	v_and_b32_e32 v93, 0xffff0000, v111
	v_pk_mul_f32 v[64:65], v[64:65], v[86:87]
	v_pk_mul_f32 v[62:63], v[62:63], v[82:83]
	v_pk_mul_f32 v[58:59], v[58:59], v[94:95]
	v_pk_mul_f32 v[60:61], v[60:61], v[96:97]
	v_pk_mul_f32 v[62:63], v[62:63], v[90:91]
	v_pk_mul_f32 v[64:65], v[64:65], v[92:93]
	v_pk_mul_f32 v[82:83], v[60:61], v[80:81] op_sel_hi:[1,0]
	v_pk_mul_f32 v[60:61], v[58:59], v[80:81] op_sel_hi:[1,0]
	v_pk_mul_f32 v[64:65], v[64:65], v[80:81] op_sel_hi:[1,0]
	v_pk_mul_f32 v[62:63], v[62:63], v[80:81] op_sel_hi:[1,0]
	v_cvt_pk_bf16_f32 v60, v60, v61
	v_mul_f32_e32 v61, 0xbfb8aa3b, v54
	v_cvt_pk_bf16_f32 v58, v62, v63
	v_cvt_pk_bf16_f32 v59, v64, v65
	v_exp_f32_e32 v62, v61
	v_mul_f32_e32 v61, 0xbfb8aa3b, v50
	v_mul_f32_e32 v64, 0xbfb8aa3b, v55
	v_exp_f32_e32 v63, v61
	v_exp_f32_e32 v65, v64
	v_mul_f32_e32 v64, 0xbfb8aa3b, v51
	v_exp_f32_e32 v79, v64
	v_add_f32_e32 v63, 1.0, v63
	v_rcp_f32_e32 v64, v63
	v_add_f32_e32 v63, 1.0, v65
	v_add_f32_e32 v65, 1.0, v79
	v_mul_f32_e32 v79, 0xbfb8aa3b, v56
	v_exp_f32_e32 v79, v79
	v_mul_f32_e32 v81, 0xbfb8aa3b, v52
	v_exp_f32_e32 v81, v81
	v_cvt_pk_bf16_f32 v61, v82, v83
	v_add_f32_e32 v79, 1.0, v79
	v_rcp_f32_e32 v82, v79
	v_add_f32_e32 v79, 1.0, v81
	v_mul_f32_e32 v81, 0xbfb8aa3b, v57
	v_exp_f32_e32 v81, v81
	v_mul_f32_e32 v83, 0xbfb8aa3b, v53
	v_exp_f32_e32 v85, v83
	v_rcp_f32_e32 v84, v79
	v_add_f32_e32 v79, 1.0, v81
	v_rcp_f32_e32 v83, v79
	v_add_f32_e32 v79, 1.0, v85
	v_add_f32_e32 v62, 1.0, v62
	v_rcp_f32_e32 v65, v65
	v_rcp_f32_e32 v85, v79
	v_rcp_f32_e32 v62, v62
	v_rcp_f32_e32 v63, v63
	v_lshlrev_b32_e32 v90, 16, v104
	v_and_b32_e32 v91, 0xffff0000, v104
	v_lshlrev_b32_e32 v92, 16, v105
	v_and_b32_e32 v93, 0xffff0000, v105
	v_pk_mul_f32 v[52:53], v[52:53], v[84:85]
	v_pk_mul_f32 v[50:51], v[50:51], v[64:65]
	v_lshlrev_b32_e32 v86, 16, v102
	v_and_b32_e32 v87, 0xffff0000, v102
	v_pk_mul_f32 v[54:55], v[54:55], v[62:63]
	v_pk_mul_f32 v[50:51], v[50:51], v[90:91]
	v_pk_mul_f32 v[52:53], v[52:53], v[92:93]
	v_lshlrev_b32_e32 v88, 16, v103
	v_and_b32_e32 v89, 0xffff0000, v103
	v_pk_mul_f32 v[56:57], v[56:57], v[82:83]
	v_pk_mul_f32 v[54:55], v[54:55], v[86:87]
	v_pk_mul_f32 v[62:63], v[52:53], v[80:81] op_sel_hi:[1,0]
	v_pk_mul_f32 v[52:53], v[50:51], v[80:81] op_sel_hi:[1,0]
	v_pk_mul_f32 v[56:57], v[56:57], v[88:89]
	v_pk_mul_f32 v[54:55], v[54:55], v[80:81] op_sel_hi:[1,0]
	v_cvt_pk_bf16_f32 v52, v52, v53
	v_mul_f32_e32 v53, 0xbfb8aa3b, v46
	v_pk_mul_f32 v[56:57], v[56:57], v[80:81] op_sel_hi:[1,0]
	v_cvt_pk_bf16_f32 v50, v54, v55
	v_exp_f32_e32 v54, v53
	v_mul_f32_e32 v53, 0xbfb8aa3b, v42
	v_cvt_pk_bf16_f32 v51, v56, v57
	v_exp_f32_e32 v55, v53
	v_mul_f32_e32 v56, 0xbfb8aa3b, v47
	v_mul_f32_e32 v57, 0xbfb8aa3b, v43
	v_exp_f32_e32 v56, v56
	v_exp_f32_e32 v57, v57
	v_add_f32_e32 v55, 1.0, v55
	v_cvt_pk_bf16_f32 v53, v62, v63
	v_rcp_f32_e32 v62, v55
	v_add_f32_e32 v55, 1.0, v56
	v_add_f32_e32 v56, 1.0, v57
	v_mul_f32_e32 v57, 0xbfb8aa3b, v48
	v_mul_f32_e32 v63, 0xbfb8aa3b, v44
	v_exp_f32_e32 v57, v57
	v_exp_f32_e32 v64, v63
	v_rcp_f32_e32 v63, v56
	v_add_f32_e32 v54, 1.0, v54
	v_add_f32_e32 v56, 1.0, v57
	v_add_f32_e32 v57, 1.0, v64
	v_mul_f32_e32 v64, 0xbfb8aa3b, v49
	v_exp_f32_e32 v65, v64
	v_mul_f32_e32 v64, 0xbfb8aa3b, v45
	v_exp_f32_e32 v79, v64
	v_rcp_f32_e32 v64, v57
	v_add_f32_e32 v57, 1.0, v65
	v_rcp_f32_e32 v54, v54
	v_rcp_f32_e32 v55, v55
	v_rcp_f32_e32 v56, v56
	v_rcp_f32_e32 v57, v57
	v_lshlrev_b32_e32 v80, 16, v70
	v_and_b32_e32 v81, 0xffff0000, v70
	v_lshlrev_b32_e32 v70, 16, v71
	v_and_b32_e32 v71, 0xffff0000, v71
	v_pk_mul_f32 v[48:49], v[48:49], v[56:57]
	v_pk_mul_f32 v[46:47], v[46:47], v[54:55]
	v_add_u32_e32 v84, 0xb0, v146
	v_add_u32_e32 v86, 0xa0, v146
	v_pk_mul_f32 v[80:81], v[46:47], v[80:81]
	v_pk_mul_f32 v[46:47], v[48:49], v[70:71]
	v_ashrrev_i32_e32 v85, 31, v84
	v_ashrrev_i32_e32 v87, 31, v86
	v_pk_mul_f32 v[70:71], v[46:47], v[78:79] op_sel_hi:[1,0]
	v_lshlrev_b64 v[46:47], 8, v[84:85]
	v_lshlrev_b64 v[48:49], 8, v[86:87]
	v_lshl_add_u64 v[46:47], v[152:153], 0, v[46:47]
	v_lshl_add_u64 v[54:55], v[152:153], 0, v[48:49]
	s_nop 0
	v_add_f32_e32 v65, 1.0, v79
	v_rcp_f32_e32 v65, v65
	v_lshlrev_b32_e32 v82, 16, v72
	v_and_b32_e32 v83, 0xffff0000, v72
	v_lshlrev_b32_e32 v72, 16, v73
	v_and_b32_e32 v73, 0xffff0000, v73
	v_pk_mul_f32 v[44:45], v[44:45], v[64:65]
	v_pk_mul_f32 v[42:43], v[42:43], v[62:63]
	v_pk_mul_f32 v[44:45], v[44:45], v[72:73]
	v_pk_mul_f32 v[42:43], v[42:43], v[82:83]
	v_pk_mul_f32 v[44:45], v[44:45], v[78:79] op_sel_hi:[1,0]
	v_pk_mul_f32 v[42:43], v[42:43], v[78:79] op_sel_hi:[1,0]
	v_cvt_pk_bf16_f32 v65, v44, v45
	v_cvt_pk_bf16_f32 v64, v42, v43
	v_mul_f32_e32 v43, 0xbfb8aa3b, v34
	v_mul_f32_e32 v44, 0xbfb8aa3b, v39
	v_exp_f32_e32 v43, v43
	v_exp_f32_e32 v45, v44
	v_mul_f32_e32 v44, 0xbfb8aa3b, v35
	v_cvt_pk_bf16_f32 v63, v70, v71
	v_exp_f32_e32 v70, v44
	v_add_f32_e32 v43, 1.0, v43
	v_rcp_f32_e32 v44, v43
	v_add_f32_e32 v43, 1.0, v45
	v_add_f32_e32 v45, 1.0, v70
	v_mul_f32_e32 v70, 0xbfb8aa3b, v40
	v_exp_f32_e32 v70, v70
	v_mul_f32_e32 v71, 0xbfb8aa3b, v36
	v_exp_f32_e32 v71, v71
	v_pk_mul_f32 v[80:81], v[80:81], v[78:79] op_sel_hi:[1,0]
	v_add_f32_e32 v70, 1.0, v70
	v_cvt_pk_bf16_f32 v62, v80, v81
	v_rcp_f32_e32 v80, v70
	v_add_f32_e32 v70, 1.0, v71
	v_rcp_f32_e32 v82, v70
	v_mul_f32_e32 v70, 0xbfb8aa3b, v41
	v_exp_f32_e32 v79, v70
	v_mul_f32_e32 v70, 0xbfb8aa3b, v37
	v_exp_f32_e32 v83, v70
	v_lshlrev_b64 v[70:71], 12, v[84:85]
	v_lshl_add_u64 v[152:153], v[150:151], 0, v[70:71]
	v_mul_f32_e32 v42, 0xbfb8aa3b, v38
	v_exp_f32_e32 v42, v42
	v_add_f32_e32 v79, 1.0, v79
	v_rcp_f32_e32 v81, v79
	v_add_f32_e32 v79, 1.0, v83
	v_add_f32_e32 v42, 1.0, v42
	v_rcp_f32_e32 v42, v42
	v_rcp_f32_e32 v43, v43
	v_rcp_f32_e32 v45, v45
	v_rcp_f32_e32 v83, v79
	v_lshlrev_b32_e32 v84, 16, v66
	v_and_b32_e32 v85, 0xffff0000, v66
	v_lshlrev_b32_e32 v66, 16, v67
	v_and_b32_e32 v67, 0xffff0000, v67
	v_lshlrev_b32_e32 v88, 16, v68
	v_and_b32_e32 v89, 0xffff0000, v68
	v_lshlrev_b32_e32 v68, 16, v69
	v_and_b32_e32 v69, 0xffff0000, v69
	v_pk_mul_f32 v[40:41], v[40:41], v[80:81]
	v_pk_mul_f32 v[38:39], v[38:39], v[42:43]
	v_pk_mul_f32 v[36:37], v[36:37], v[82:83]
	v_pk_mul_f32 v[34:35], v[34:35], v[44:45]
	v_pk_mul_f32 v[38:39], v[38:39], v[84:85]
	v_pk_mul_f32 v[40:41], v[40:41], v[66:67]
	v_pk_mul_f32 v[34:35], v[34:35], v[88:89]
	v_pk_mul_f32 v[36:37], v[36:37], v[68:69]
	v_pk_mul_f32 v[40:41], v[40:41], v[78:79] op_sel_hi:[1,0]
	v_pk_mul_f32 v[38:39], v[38:39], v[78:79] op_sel_hi:[1,0]
	v_pk_mul_f32 v[36:37], v[36:37], v[78:79] op_sel_hi:[1,0]
	v_pk_mul_f32 v[34:35], v[34:35], v[78:79] op_sel_hi:[1,0]
	v_cvt_pk_bf16_f32 v68, v34, v35
	v_lshlrev_b64 v[34:35], 12, v[86:87]
	v_lshl_add_u64 v[42:43], v[150:151], 0, v[34:35]
	v_cvt_pk_bf16_f32 v66, v38, v39
	v_cvt_pk_bf16_f32 v67, v40, v41
	v_cvt_pk_bf16_f32 v69, v36, v37
	s_waitcnt vmcnt(4)
	v_mov_b32_e32 v46, v226
	v_mov_b32_e32 v47, v227
	v_mov_b32_e32 v48, v228
	v_mov_b32_e32 v49, v229
	v_mov_b32_e32 v54, v230
	v_mov_b32_e32 v55, v231
	v_mov_b32_e32 v56, v232
	v_mov_b32_e32 v57, v233
	v_mov_b32_e32 v70, v242
	v_mov_b32_e32 v71, v243
	v_mov_b32_e32 v72, v244
	v_mov_b32_e32 v73, v245
	v_mov_b32_e32 v78, v246
	v_mov_b32_e32 v79, v247
	v_mov_b32_e32 v80, v248
	v_mov_b32_e32 v81, v249
	v_mov_b32_e32 v38, v234
	v_mov_b32_e32 v39, v235
	v_mov_b32_e32 v40, v236
	v_mov_b32_e32 v41, v237
	v_mov_b32_e32 v34, v238
	v_mov_b32_e32 v35, v239
	v_mov_b32_e32 v36, v240
	v_mov_b32_e32 v37, v241
	s_nop 0
	global_store_dwordx4 v[74:75], v[58:61], off
	global_store_dwordx4 v[74:75], v[50:53], off offset:256
	global_store_dwordx4 v[76:77], v[62:65], off
	global_store_dwordx4 v[76:77], v[66:69], off offset:256
	s_waitcnt vmcnt(8)
	v_mov_b32_e32 v52, v47
	v_mov_b32_e32 v53, v48
	v_mov_b32_e32 v47, v49
	v_mov_b32_e32 v44, v55
	v_mov_b32_e32 v45, v56
	v_mov_b32_e32 v55, v57
	v_pk_add_f32 v[46:47], v[52:53], v[46:47]
	v_pk_add_f32 v[44:45], v[44:45], v[54:55]
	v_pk_add_f32 v[46:47], v[46:47], v[46:47] op_sel:[0,1] op_sel_hi:[1,0]
	v_pk_add_f32 v[44:45], v[44:45], v[44:45] op_sel:[0,1] op_sel_hi:[1,0]
	v_mul_f32_e32 v47, 0xbfb8aa3b, v30
	v_mov_b32_e32 v45, v44
	v_exp_f32_e32 v47, v47
	s_nop 0
	v_permlane16_swap_b32_e32 v44, v45
	v_add_f32_e32 v44, v44, v45
	v_mov_b32_e32 v45, v46
	s_nop 1
	v_permlane16_swap_b32_e32 v46, v45
	v_add_f32_e32 v45, v46, v45
	v_add_f32_e32 v46, 1.0, v47
	v_mul_f32_e32 v47, 0xbfb8aa3b, v31
	v_exp_f32_e32 v47, v47
	v_rcp_f32_e32 v46, v46
	v_mul_f32_e32 v53, 0xbfb8aa3b, v27
	v_exp_f32_e32 v53, v53
	v_add_f32_e32 v47, 1.0, v47
	v_rcp_f32_e32 v47, v47
	v_mul_f32_e32 v54, 0xbfb8aa3b, v28
	v_mul_f32_e32 v55, 0xbfb8aa3b, v29
	v_exp_f32_e32 v54, v54
	v_pk_mul_f32 v[30:31], v[30:31], v[46:47]
	v_mul_f32_e32 v47, 0xbfb8aa3b, v26
	v_exp_f32_e32 v52, v47
	v_exp_f32_e32 v55, v55
	v_add_f32_e32 v53, 1.0, v53
	v_add_f32_e32 v54, 1.0, v54
	v_add_f32_e32 v52, 1.0, v52
	v_rcp_f32_e32 v52, v52
	v_add_f32_e32 v55, 1.0, v55
	v_rcp_f32_e32 v53, v53
	v_rcp_f32_e32 v54, v54
	v_rcp_f32_e32 v55, v55
	v_lshlrev_b32_e32 v46, 16, v70
	v_and_b32_e32 v47, 0xffff0000, v70
	v_pk_mul_f32 v[30:31], v[30:31], v[46:47]
	v_pk_mul_f32 v[26:27], v[26:27], v[52:53]
	v_mul_f32_e32 v47, 0xbfb8aa3b, v22
	v_mul_f32_e32 v53, 0xbfb8aa3b, v23
	v_pk_mul_f32 v[28:29], v[28:29], v[54:55]
	v_exp_f32_e32 v52, v47
	v_exp_f32_e32 v53, v53
	v_mul_f32_e32 v54, 0xbfb8aa3b, v24
	v_mul_f32_e32 v55, 0xbfb8aa3b, v25
	v_mul_f32_e32 v48, 0xbfb8aa3b, v32
	v_mul_f32_e32 v49, 0xbfb8aa3b, v33
	v_exp_f32_e32 v54, v54
	v_exp_f32_e32 v55, v55
	v_exp_f32_e32 v48, v48
	v_exp_f32_e32 v49, v49
	v_add_f32_e32 v52, 1.0, v52
	v_add_f32_e32 v53, 1.0, v53
	v_rcp_f32_e32 v52, v52
	v_add_f32_e32 v54, 1.0, v54
	v_add_f32_e32 v55, 1.0, v55
	v_rcp_f32_e32 v53, v53
	v_add_f32_e32 v48, 1.0, v48
	v_add_f32_e32 v49, 1.0, v49
	v_rcp_f32_e32 v54, v54
	v_rcp_f32_e32 v55, v55
	v_rcp_f32_e32 v48, v48
	v_rcp_f32_e32 v49, v49
	v_lshlrev_b32_e32 v46, 16, v72
	v_and_b32_e32 v47, 0xffff0000, v72
	v_pk_mul_f32 v[26:27], v[26:27], v[46:47]
	v_pk_mul_f32 v[22:23], v[22:23], v[52:53]
	v_mul_f32_e32 v47, 0xbfb8aa3b, v18
	v_mul_f32_e32 v53, 0xbfb8aa3b, v19
	v_mov_b32_e32 v50, v44
	v_mov_b32_e32 v51, v45
	v_pk_mul_f32 v[24:25], v[24:25], v[54:55]
	v_exp_f32_e32 v52, v47
	v_exp_f32_e32 v53, v53
	v_mul_f32_e32 v54, 0xbfb8aa3b, v20
	v_mul_f32_e32 v55, 0xbfb8aa3b, v21
	v_permlane32_swap_b32_e32 v44, v50
	v_permlane32_swap_b32_e32 v45, v51
	v_pk_mul_f32 v[32:33], v[32:33], v[48:49]
	v_lshlrev_b32_e32 v48, 16, v71
	v_and_b32_e32 v49, 0xffff0000, v71
	v_exp_f32_e32 v54, v54
	v_exp_f32_e32 v55, v55
	v_pk_mul_f32 v[32:33], v[32:33], v[48:49]
	v_lshlrev_b32_e32 v48, 16, v73
	v_and_b32_e32 v49, 0xffff0000, v73
	v_pk_add_f32 v[44:45], v[44:45], v[50:51]
	v_pk_mul_f32 v[28:29], v[28:29], v[48:49]
	v_lshlrev_b32_e32 v48, 16, v79
	v_and_b32_e32 v49, 0xffff0000, v79
	v_pk_fma_f32 v[44:45], v[44:45], s[36:37], v[148:149] op_sel_hi:[1,0,0]
	v_add_f32_e32 v52, 1.0, v52
	v_add_f32_e32 v53, 1.0, v53
	v_pk_mul_f32 v[24:25], v[24:25], v[48:49]
	v_mul_f32_e32 v49, 0x4b800000, v45
	v_cmp_gt_f32_e32 vcc, s76, v45
	v_rcp_f32_e32 v52, v52
	v_add_f32_e32 v54, 1.0, v54
	v_add_f32_e32 v55, 1.0, v55
	v_rcp_f32_e32 v53, v53
	v_cndmask_b32_e32 v45, v45, v49, vcc
	v_rcp_f32_e32 v54, v54
	v_rcp_f32_e32 v55, v55
	v_rsq_f32_e32 v45, v45
	v_lshlrev_b32_e32 v46, 16, v78
	v_and_b32_e32 v47, 0xffff0000, v78
	v_pk_mul_f32 v[22:23], v[22:23], v[46:47]
	v_pk_mul_f32 v[18:19], v[18:19], v[52:53]
	v_lshlrev_b32_e32 v46, 16, v80
	v_and_b32_e32 v47, 0xffff0000, v80
	v_pk_mul_f32 v[20:21], v[20:21], v[54:55]
	v_lshlrev_b32_e32 v48, 16, v81
	v_and_b32_e32 v49, 0xffff0000, v81
	v_pk_mul_f32 v[46:47], v[18:19], v[46:47]
	v_mul_f32_e32 v18, 0x45800000, v45
	v_pk_mul_f32 v[20:21], v[20:21], v[48:49]
	v_cndmask_b32_e32 v48, v45, v18, vcc
	v_pk_mul_f32 v[18:19], v[32:33], v[48:49] op_sel_hi:[1,0]
	v_cmp_gt_f32_e32 vcc, s76, v44
	v_cvt_pk_bf16_f32 v131, v18, v19
	v_pk_mul_f32 v[18:19], v[28:29], v[48:49] op_sel_hi:[1,0]
	v_pk_mul_f32 v[26:27], v[26:27], v[48:49] op_sel_hi:[1,0]
	v_cvt_pk_bf16_f32 v133, v18, v19
	v_pk_mul_f32 v[18:19], v[22:23], v[48:49] op_sel_hi:[1,0]
	v_pk_mul_f32 v[22:23], v[20:21], v[48:49] op_sel_hi:[1,0]
	v_pk_mul_f32 v[20:21], v[46:47], v[48:49] op_sel_hi:[1,0]
	v_cvt_pk_bf16_f32 v132, v26, v27
	v_cvt_pk_bf16_f32 v20, v20, v21
	v_cvt_pk_bf16_f32 v21, v22, v23
	v_mul_f32_e32 v23, 0xbfb8aa3b, v14
	v_exp_f32_e32 v23, v23
	v_mul_f32_e32 v22, 0x4b800000, v44
	v_cndmask_b32_e32 v22, v44, v22, vcc
	v_rsq_f32_e32 v26, v22
	v_add_f32_e32 v22, 1.0, v23
	v_mul_f32_e32 v23, 0xbfb8aa3b, v15
	v_exp_f32_e32 v23, v23
	v_pk_mul_f32 v[24:25], v[24:25], v[48:49] op_sel_hi:[1,0]
	v_cvt_pk_bf16_f32 v18, v18, v19
	v_cvt_pk_bf16_f32 v19, v24, v25
	v_add_f32_e32 v23, 1.0, v23
	v_rcp_f32_e32 v22, v22
	v_mul_f32_e32 v24, 0xbfb8aa3b, v16
	v_mul_f32_e32 v25, 0xbfb8aa3b, v17
	v_rcp_f32_e32 v23, v23
	v_exp_f32_e32 v24, v24
	v_exp_f32_e32 v25, v25
	v_mul_f32_e32 v27, 0x45800000, v26
	v_pk_mul_f32 v[14:15], v[14:15], v[22:23]
	v_lshlrev_b32_e32 v22, 16, v38
	v_and_b32_e32 v23, 0xffff0000, v38
	v_add_f32_e32 v24, 1.0, v24
	v_add_f32_e32 v25, 1.0, v25
	v_pk_mul_f32 v[14:15], v[14:15], v[22:23]
	v_mul_f32_e32 v22, 0xbfb8aa3b, v10
	v_mul_f32_e32 v23, 0xbfb8aa3b, v11
	v_rcp_f32_e32 v24, v24
	v_rcp_f32_e32 v25, v25
	v_exp_f32_e32 v22, v22
	v_exp_f32_e32 v23, v23
	v_cndmask_b32_e32 v26, v26, v27, vcc
	v_pk_mul_f32 v[16:17], v[16:17], v[24:25]
	v_lshlrev_b32_e32 v24, 16, v39
	v_and_b32_e32 v25, 0xffff0000, v39
	v_add_f32_e32 v22, 1.0, v22
	v_add_f32_e32 v23, 1.0, v23
	v_pk_mul_f32 v[16:17], v[16:17], v[24:25]
	v_rcp_f32_e32 v22, v22
	v_mul_f32_e32 v24, 0xbfb8aa3b, v12
	v_mul_f32_e32 v25, 0xbfb8aa3b, v13
	v_rcp_f32_e32 v23, v23
	v_exp_f32_e32 v24, v24
	v_exp_f32_e32 v25, v25
	v_pk_mul_f32 v[16:17], v[16:17], v[26:27] op_sel_hi:[1,0]
	v_pk_mul_f32 v[14:15], v[14:15], v[26:27] op_sel_hi:[1,0]
	v_pk_mul_f32 v[10:11], v[10:11], v[22:23]
	v_cvt_pk_bf16_f32 v14, v14, v15
	v_cvt_pk_bf16_f32 v15, v16, v17
	v_lshlrev_b32_e32 v16, 16, v40
	v_and_b32_e32 v17, 0xffff0000, v40
	v_add_f32_e32 v24, 1.0, v24
	v_add_f32_e32 v25, 1.0, v25
	v_pk_mul_f32 v[10:11], v[10:11], v[16:17]
	v_mul_f32_e32 v16, 0xbfb8aa3b, v6
	v_rcp_f32_e32 v24, v24
	v_rcp_f32_e32 v25, v25
	v_exp_f32_e32 v16, v16
	v_lshlrev_b32_e32 v22, 16, v41
	v_and_b32_e32 v23, 0xffff0000, v41
	v_pk_mul_f32 v[12:13], v[12:13], v[24:25]
	v_add_f32_e32 v16, 1.0, v16
	v_mul_f32_e32 v17, 0xbfb8aa3b, v8
	v_pk_mul_f32 v[12:13], v[12:13], v[22:23]
	v_rcp_f32_e32 v22, v16
	v_mul_f32_e32 v16, 0xbfb8aa3b, v7
	v_exp_f32_e32 v17, v17
	v_mul_f32_e32 v23, 0xbfb8aa3b, v9
	v_exp_f32_e32 v16, v16
	v_exp_f32_e32 v23, v23
	v_add_f32_e32 v17, 1.0, v17
	v_rcp_f32_e32 v24, v17
	v_add_f32_e32 v16, 1.0, v16
	v_add_f32_e32 v17, 1.0, v23
	v_rcp_f32_e32 v25, v17
	v_rcp_f32_e32 v23, v16
	v_pk_mul_f32 v[12:13], v[12:13], v[26:27] op_sel_hi:[1,0]
	v_pk_mul_f32 v[10:11], v[10:11], v[26:27] op_sel_hi:[1,0]
	v_cvt_pk_bf16_f32 v17, v12, v13
	v_cvt_pk_bf16_f32 v16, v10, v11
	v_pk_mul_f32 v[8:9], v[8:9], v[24:25]
	v_pk_mul_f32 v[6:7], v[6:7], v[22:23]
	v_lshlrev_b32_e32 v10, 16, v34
	v_and_b32_e32 v11, 0xffff0000, v34
	v_lshlrev_b32_e32 v12, 16, v35
	v_and_b32_e32 v13, 0xffff0000, v35
	v_pk_mul_f32 v[6:7], v[6:7], v[10:11]
	v_mul_f32_e32 v10, 0xbfb8aa3b, v2
	v_pk_mul_f32 v[8:9], v[8:9], v[12:13]
	v_mul_f32_e32 v11, 0xbfb8aa3b, v3
	v_mul_f32_e32 v12, 0xbfb8aa3b, v4
	v_mul_f32_e32 v13, 0xbfb8aa3b, v5
	v_exp_f32_e32 v10, v10
	v_exp_f32_e32 v11, v11
	v_exp_f32_e32 v12, v12
	v_exp_f32_e32 v13, v13
	v_add_f32_e32 v10, 1.0, v10
	v_add_f32_e32 v11, 1.0, v11
	v_add_f32_e32 v12, 1.0, v12
	v_add_f32_e32 v13, 1.0, v13
	v_rcp_f32_e32 v10, v10
	v_rcp_f32_e32 v12, v12
	v_rcp_f32_e32 v13, v13
	v_rcp_f32_e32 v11, v11
	v_pk_mul_f32 v[8:9], v[8:9], v[26:27] op_sel_hi:[1,0]
	v_pk_mul_f32 v[6:7], v[6:7], v[26:27] op_sel_hi:[1,0]
	v_pk_mul_f32 v[4:5], v[4:5], v[12:13]
	v_cvt_pk_bf16_f32 v6, v6, v7
	v_cvt_pk_bf16_f32 v7, v8, v9
	v_pk_mul_f32 v[2:3], v[2:3], v[10:11]
	v_lshlrev_b32_e32 v8, 16, v36
	v_and_b32_e32 v9, 0xffff0000, v36
	v_lshlrev_b32_e32 v10, 16, v37
	v_and_b32_e32 v11, 0xffff0000, v37
	v_pk_mul_f32 v[2:3], v[2:3], v[8:9]
	v_pk_mul_f32 v[4:5], v[4:5], v[10:11]
	v_pk_mul_f32 v[30:31], v[30:31], v[48:49] op_sel_hi:[1,0]
	v_pk_mul_f32 v[4:5], v[4:5], v[26:27] op_sel_hi:[1,0]
	v_pk_mul_f32 v[2:3], v[2:3], v[26:27] op_sel_hi:[1,0]
	v_cvt_pk_bf16_f32 v130, v30, v31
	v_cvt_pk_bf16_f32 v8, v2, v3
	v_cvt_pk_bf16_f32 v9, v4, v5
	global_store_dwordx4 v[42:43], v[6:9], off
	global_store_dwordx4 v[42:43], v[14:17], off offset:256
	global_store_dwordx4 v[152:153], v[18:21], off
	s_andn2_b64 vcc, exec, s[2:3]
	s_mov_b64 s[0:1], -1
	global_store_dwordx4 v[152:153], v[130:133], off offset:256
	s_cbranch_vccnz .LBB0_678
